# lru_fix output loop: the 12 row loads of each unrolled body issued together (was 4 serialized load-wait-store steps)
# speedup vs baseline: 1.0060x; 1.0032x over previous
; __device__ __forceinline__ unsigned pk2(float lo, float hi) { f32x2 v = {lo, hi}; bf16x2_t b = __builtin_convertvector(v, bf16x2_t); return __builtin_bit_cast(unsigned, b); }
; __device__ __forceinline__ float bf_lo(unsigned u) { return __uint_as_float(u << 16); }
; __device__ __forceinline__ float bf_hi(unsigned u) { return __uint_as_float(u & 0xffff0000u); }
; __device__ __forceinline__ void lru_fix_item(const Ptrs& P, int it) {
;     ...
; #pragma unroll 4
;     for (int k = 0; k < 16; ++k) { const size_t row = (size_t)(b * SEQ + c * 64 + tg + 4 * k);
;         const u32x4 hw = *(const u32x4*)(P.HL() + row * 1024 + c8 * 8), cw = *(const u32x4*)(P.CA() + row * 1024 + c8 * 8), gw = *(const u32x4*)(P.PA() + row * NA + C_GC + c8 * 8);
;         u32x4 o;
;         o.x = pk2((bf_lo(hw.x) + bf_lo(cw.x) * H0[0]) * bf_lo(gw.x), (bf_hi(hw.x) + bf_hi(cw.x) * H0[1]) * bf_hi(gw.x));
;         o.y = pk2((bf_lo(hw.y) + bf_lo(cw.y) * H0[2]) * bf_lo(gw.y), (bf_hi(hw.y) + bf_hi(cw.y) * H0[3]) * bf_hi(gw.y));
;         o.z = pk2((bf_lo(hw.z) + bf_lo(cw.z) * H1[0]) * bf_lo(gw.z), (bf_hi(hw.z) + bf_hi(cw.z) * H1[1]) * bf_hi(gw.z));
;         o.w = pk2((bf_lo(hw.w) + bf_lo(cw.w) * H1[2]) * bf_lo(gw.w), (bf_hi(hw.w) + bf_hi(cw.w) * H1[3]) * bf_hi(gw.w));
;         *(u32x4*)(P.YC() + row * 1024 + c8 * 8) = o; }
.LBB0_781:
	s_nop 0
	v_add_u32_e32 v18, s0, v1
	v_mov_b64_e32 v[20:21], s[14:15]
	v_mad_i64_i32 v[24:25], s[64:65], v18, s41, v[20:21]
	v_add_u32_e32 v26, 4, v18
	v_lshl_add_u64 v[32:33], v[24:25], 0, v[2:3]
	v_mad_i64_i32 v[24:25], s[64:65], v26, s41, v[20:21]
	v_add_co_u32_e32 v32, vcc, s42, v32
	v_ashrrev_i32_e32 v19, 31, v18
	v_add_u32_e32 v28, 8, v18
	v_lshl_add_u64 v[44:45], v[24:25], 0, v[2:3]
	v_addc_co_u32_e32 v33, vcc, 0, v33, vcc
	v_lshlrev_b64 v[30:31], 11, v[18:19]
	v_mad_i64_i32 v[34:35], s[64:65], v28, s41, v[20:21]
	v_add_co_u32_e32 v44, vcc, s42, v44
	v_ashrrev_i32_e32 v27, 31, v26
	v_ashrrev_i32_e32 v29, 31, v28
	v_lshl_add_u64 v[36:37], v[12:13], 0, v[30:31]
	v_lshl_add_u64 v[34:35], v[34:35], 0, v[2:3]
	v_addc_co_u32_e32 v45, vcc, 0, v45, vcc
	v_lshl_add_u64 v[38:39], v[14:15], 0, v[30:31]
	v_lshl_add_u64 v[40:41], v[16:17], 0, v[30:31]
	v_lshlrev_b64 v[42:43], 11, v[26:27]
	v_lshlrev_b64 v[46:47], 11, v[28:29]
	global_load_dwordx4 v[24:27], v[36:37], off
	global_load_dwordx4 v[28:31], v[38:39], off
	v_add_co_u32_e32 v52, vcc, s42, v34
	v_lshl_add_u64 v[36:37], v[12:13], 0, v[42:43]
	s_nop 0
	v_addc_co_u32_e32 v53, vcc, 0, v35, vcc
	global_load_dwordx4 v[32:35], v[32:33], off offset:3072
	v_lshl_add_u64 v[38:39], v[14:15], 0, v[42:43]
	v_lshl_add_u64 v[42:43], v[16:17], 0, v[42:43]
	v_lshl_add_u64 v[48:49], v[12:13], 0, v[46:47]
	v_lshl_add_u64 v[50:51], v[14:15], 0, v[46:47]
	v_add_u32_e32 v18, 12, v18
	v_ashrrev_i32_e32 v19, 31, v18
	v_mad_i64_i32 v[20:21], s[64:65], v18, s41, v[20:21]
	s_add_i32 s0, s0, 16
	s_cmp_lg_u32 s0, 64
	global_load_dwordx4 v[156:159], v[36:37], off
	global_load_dwordx4 v[160:163], v[38:39], off
	global_load_dwordx4 v[164:167], v[44:45], off offset:3072
	global_load_dwordx4 v[168:171], v[48:49], off
	global_load_dwordx4 v[172:175], v[50:51], off
	global_load_dwordx4 v[176:179], v[52:53], off offset:3072
	v_lshlrev_b64 v[192:193], 11, v[18:19]
	v_lshl_add_u64 v[194:195], v[20:21], 0, v[2:3]
	v_add_co_u32_e32 v198, vcc, s42, v194
	v_addc_co_u32_e32 v199, vcc, 0, v195, vcc
	v_lshl_add_u64 v[194:195], v[12:13], 0, v[192:193]
	v_lshl_add_u64 v[196:197], v[14:15], 0, v[192:193]
	global_load_dwordx4 v[180:183], v[194:195], off
	global_load_dwordx4 v[184:187], v[196:197], off
	global_load_dwordx4 v[188:191], v[198:199], off offset:3072
	s_waitcnt vmcnt(11)
	v_lshlrev_b32_e32 v54, 16, v24
	v_and_b32_e32 v55, 0xffff0000, v24
	s_waitcnt vmcnt(10)
	v_lshlrev_b32_e32 v56, 16, v28
	v_and_b32_e32 v57, 0xffff0000, v28
	v_lshlrev_b32_e32 v24, 16, v25
	v_and_b32_e32 v25, 0xffff0000, v25
	v_lshlrev_b32_e32 v28, 16, v29
	v_and_b32_e32 v29, 0xffff0000, v29
	v_lshlrev_b32_e32 v58, 16, v26
	v_and_b32_e32 v59, 0xffff0000, v26
	v_lshlrev_b32_e32 v60, 16, v30
	v_and_b32_e32 v61, 0xffff0000, v30
	v_lshlrev_b32_e32 v26, 16, v27
	v_and_b32_e32 v27, 0xffff0000, v27
	v_lshlrev_b32_e32 v30, 16, v31
	v_and_b32_e32 v31, 0xffff0000, v31
	v_pk_fma_f32 v[54:55], v[4:5], v[56:57], v[54:55]
	s_waitcnt vmcnt(9)
	v_lshlrev_b32_e32 v56, 16, v32
	v_and_b32_e32 v57, 0xffff0000, v32
	v_pk_fma_f32 v[24:25], v[6:7], v[28:29], v[24:25]
	v_lshlrev_b32_e32 v28, 16, v33
	v_and_b32_e32 v29, 0xffff0000, v33
	v_pk_fma_f32 v[32:33], v[8:9], v[60:61], v[58:59]
	v_lshlrev_b32_e32 v58, 16, v34
	v_and_b32_e32 v59, 0xffff0000, v34
	v_pk_fma_f32 v[26:27], v[10:11], v[30:31], v[26:27]
	v_lshlrev_b32_e32 v30, 16, v35
	v_and_b32_e32 v31, 0xffff0000, v35
	v_pk_mul_f32 v[34:35], v[54:55], v[56:57]
	v_pk_mul_f32 v[28:29], v[24:25], v[28:29]
	v_pk_mul_f32 v[32:33], v[32:33], v[58:59]
	v_pk_mul_f32 v[30:31], v[26:27], v[30:31]
	v_cvt_pk_bf16_f32 v24, v34, v35
	v_cvt_pk_bf16_f32 v25, v28, v29
	v_cvt_pk_bf16_f32 v26, v32, v33
	v_cvt_pk_bf16_f32 v27, v30, v31
	global_store_dwordx4 v[40:41], v[24:27], off
	s_nop 0
	s_nop 0
	s_nop 0
	s_nop 0
	s_waitcnt vmcnt(9)
	v_lshlrev_b32_e32 v36, 16, v156
	v_and_b32_e32 v37, 0xffff0000, v156
	s_waitcnt vmcnt(8)
	v_lshlrev_b32_e32 v38, 16, v160
	v_and_b32_e32 v39, 0xffff0000, v160
	v_lshlrev_b32_e32 v24, 16, v157
	v_and_b32_e32 v25, 0xffff0000, v157
	v_lshlrev_b32_e32 v28, 16, v161
	v_and_b32_e32 v29, 0xffff0000, v161
	v_lshlrev_b32_e32 v44, 16, v158
	v_and_b32_e32 v45, 0xffff0000, v158
	v_lshlrev_b32_e32 v54, 16, v162
	v_and_b32_e32 v55, 0xffff0000, v162
	v_lshlrev_b32_e32 v26, 16, v159
	v_and_b32_e32 v27, 0xffff0000, v159
	v_lshlrev_b32_e32 v30, 16, v163
	v_and_b32_e32 v31, 0xffff0000, v163
	s_waitcnt vmcnt(7)
; __device__ __forceinline__ unsigned pk2(float lo, float hi) { f32x2 v = {lo, hi}; bf16x2_t b = __builtin_convertvector(v, bf16x2_t); return __builtin_bit_cast(unsigned, b); }
; __device__ __forceinline__ float bf_lo(unsigned u) { return __uint_as_float(u << 16); }
; __device__ __forceinline__ float bf_hi(unsigned u) { return __uint_as_float(u & 0xffff0000u); }
; __device__ __forceinline__ void lru_fix_item(const Ptrs& P, int it) {
;     ...
; #pragma unroll 4
;     for (int k = 0; k < 16; ++k) { const size_t row = (size_t)(b * SEQ + c * 64 + tg + 4 * k);
;         const u32x4 hw = *(const u32x4*)(P.HL() + row * 1024 + c8 * 8), cw = *(const u32x4*)(P.CA() + row * 1024 + c8 * 8), gw = *(const u32x4*)(P.PA() + row * NA + C_GC + c8 * 8);
;         u32x4 o;
;         o.x = pk2((bf_lo(hw.x) + bf_lo(cw.x) * H0[0]) * bf_lo(gw.x), (bf_hi(hw.x) + bf_hi(cw.x) * H0[1]) * bf_hi(gw.x));
;         o.y = pk2((bf_lo(hw.y) + bf_lo(cw.y) * H0[2]) * bf_lo(gw.y), (bf_hi(hw.y) + bf_hi(cw.y) * H0[3]) * bf_hi(gw.y));
;         o.z = pk2((bf_lo(hw.z) + bf_lo(cw.z) * H1[0]) * bf_lo(gw.z), (bf_hi(hw.z) + bf_hi(cw.z) * H1[1]) * bf_hi(gw.z));
;         o.w = pk2((bf_lo(hw.w) + bf_lo(cw.w) * H1[2]) * bf_lo(gw.w), (bf_hi(hw.w) + bf_hi(cw.w) * H1[3]) * bf_hi(gw.w));
;         *(u32x4*)(P.YC() + row * 1024 + c8 * 8) = o; }
; template <int l> __device__ __forceinline__ void layer_phases(LAS unsigned char* lds, Ptrs& P, const XcdBarrier& xbar, KArgs kargs, const int lo, const int hi, const int lane0, const int wave, const int G0, const int bx0) {
;     ...
;             for (int it = bx; it < 256; it += G) lru_fix_item(P, it);
	v_lshlrev_b32_e32 v40, 16, v164
	v_and_b32_e32 v41, 0xffff0000, v164
	v_lshlrev_b32_e32 v32, 16, v165
	v_and_b32_e32 v33, 0xffff0000, v165
	v_lshlrev_b32_e32 v56, 16, v166
	v_and_b32_e32 v57, 0xffff0000, v166
	v_lshlrev_b32_e32 v34, 16, v167
	v_and_b32_e32 v35, 0xffff0000, v167
	v_pk_fma_f32 v[36:37], v[4:5], v[38:39], v[36:37]
	v_pk_fma_f32 v[24:25], v[6:7], v[28:29], v[24:25]
	v_pk_fma_f32 v[28:29], v[8:9], v[54:55], v[44:45]
	v_pk_fma_f32 v[26:27], v[10:11], v[30:31], v[26:27]
	v_pk_mul_f32 v[30:31], v[36:37], v[40:41]
	v_pk_mul_f32 v[32:33], v[24:25], v[32:33]
	v_pk_mul_f32 v[28:29], v[28:29], v[56:57]
	v_pk_mul_f32 v[34:35], v[26:27], v[34:35]
	v_cvt_pk_bf16_f32 v24, v30, v31
	v_cvt_pk_bf16_f32 v25, v32, v33
	v_cvt_pk_bf16_f32 v26, v28, v29
	v_cvt_pk_bf16_f32 v27, v34, v35
	global_store_dwordx4 v[42:43], v[24:27], off
	s_nop 0
	s_nop 0
	s_nop 0
	s_nop 0
	v_lshlrev_b64 v[36:37], 11, v[18:19]
	v_lshl_add_u64 v[18:19], v[20:21], 0, v[2:3]
	v_add_co_u32_e32 v44, vcc, s42, v18
	v_lshl_add_u64 v[38:39], v[16:17], 0, v[46:47]
	s_nop 0
	v_addc_co_u32_e32 v45, vcc, 0, v19, vcc
	v_lshl_add_u64 v[40:41], v[12:13], 0, v[36:37]
	v_lshl_add_u64 v[42:43], v[14:15], 0, v[36:37]
	s_waitcnt vmcnt(7)
	v_lshlrev_b32_e32 v18, 16, v168
	v_and_b32_e32 v19, 0xffff0000, v168
	s_waitcnt vmcnt(6)
	v_lshlrev_b32_e32 v20, 16, v172
	v_and_b32_e32 v21, 0xffff0000, v172
	v_lshlrev_b32_e32 v24, 16, v169
	v_and_b32_e32 v25, 0xffff0000, v169
	v_lshlrev_b32_e32 v28, 16, v173
	v_and_b32_e32 v29, 0xffff0000, v173
	v_lshlrev_b32_e32 v48, 16, v170
	v_and_b32_e32 v49, 0xffff0000, v170
	v_lshlrev_b32_e32 v50, 16, v174
	v_and_b32_e32 v51, 0xffff0000, v174
	v_lshlrev_b32_e32 v26, 16, v171
	v_and_b32_e32 v27, 0xffff0000, v171
	v_lshlrev_b32_e32 v30, 16, v175
	v_and_b32_e32 v31, 0xffff0000, v175
	s_waitcnt vmcnt(5)
	v_lshlrev_b32_e32 v46, 16, v176
	v_and_b32_e32 v47, 0xffff0000, v176
	v_lshlrev_b32_e32 v32, 16, v177
	v_and_b32_e32 v33, 0xffff0000, v177
	v_lshlrev_b32_e32 v52, 16, v178
	v_and_b32_e32 v53, 0xffff0000, v178
	v_lshlrev_b32_e32 v34, 16, v179
	v_and_b32_e32 v35, 0xffff0000, v179
	v_pk_fma_f32 v[18:19], v[4:5], v[20:21], v[18:19]
	v_pk_fma_f32 v[20:21], v[6:7], v[28:29], v[24:25]
	v_pk_fma_f32 v[24:25], v[8:9], v[50:51], v[48:49]
	v_pk_fma_f32 v[26:27], v[10:11], v[30:31], v[26:27]
	v_pk_mul_f32 v[18:19], v[18:19], v[46:47]
	v_pk_mul_f32 v[20:21], v[20:21], v[32:33]
	v_pk_mul_f32 v[24:25], v[24:25], v[52:53]
	v_pk_mul_f32 v[26:27], v[26:27], v[34:35]
	v_cvt_pk_bf16_f32 v18, v18, v19
	v_cvt_pk_bf16_f32 v19, v20, v21
	v_cvt_pk_bf16_f32 v20, v24, v25
	v_cvt_pk_bf16_f32 v21, v26, v27
	global_store_dwordx4 v[38:39], v[18:21], off
	s_nop 0
	s_nop 0
	s_nop 0
	s_nop 0
	v_lshl_add_u64 v[32:33], v[16:17], 0, v[36:37]
	s_waitcnt vmcnt(5)
	v_lshlrev_b32_e32 v34, 16, v180
	v_and_b32_e32 v35, 0xffff0000, v180
	s_waitcnt vmcnt(4)
	v_lshlrev_b32_e32 v36, 16, v184
	v_and_b32_e32 v37, 0xffff0000, v184
	v_lshlrev_b32_e32 v18, 16, v181
	v_and_b32_e32 v19, 0xffff0000, v181
	v_lshlrev_b32_e32 v24, 16, v185
	v_and_b32_e32 v25, 0xffff0000, v185
	v_lshlrev_b32_e32 v40, 16, v182
	v_and_b32_e32 v41, 0xffff0000, v182
	v_lshlrev_b32_e32 v42, 16, v186
	v_and_b32_e32 v43, 0xffff0000, v186
	v_lshlrev_b32_e32 v20, 16, v183
	v_and_b32_e32 v21, 0xffff0000, v183
	v_lshlrev_b32_e32 v26, 16, v187
	v_and_b32_e32 v27, 0xffff0000, v187
	s_waitcnt vmcnt(3)
	v_lshlrev_b32_e32 v38, 16, v188
	v_and_b32_e32 v39, 0xffff0000, v188
	v_lshlrev_b32_e32 v28, 16, v189
	v_and_b32_e32 v29, 0xffff0000, v189
	v_lshlrev_b32_e32 v44, 16, v190
	v_and_b32_e32 v45, 0xffff0000, v190
	v_lshlrev_b32_e32 v30, 16, v191
	v_and_b32_e32 v31, 0xffff0000, v191
	v_pk_fma_f32 v[34:35], v[4:5], v[36:37], v[34:35]
	v_pk_fma_f32 v[18:19], v[6:7], v[24:25], v[18:19]
	v_pk_fma_f32 v[24:25], v[8:9], v[42:43], v[40:41]
	v_pk_fma_f32 v[20:21], v[10:11], v[26:27], v[20:21]
	v_pk_mul_f32 v[26:27], v[34:35], v[38:39]
	v_pk_mul_f32 v[28:29], v[18:19], v[28:29]
	v_pk_mul_f32 v[24:25], v[24:25], v[44:45]
	v_pk_mul_f32 v[30:31], v[20:21], v[30:31]
	v_cvt_pk_bf16_f32 v18, v26, v27
	v_cvt_pk_bf16_f32 v19, v28, v29
	v_cvt_pk_bf16_f32 v20, v24, v25
	v_cvt_pk_bf16_f32 v21, v30, v31
	global_store_dwordx4 v[32:33], v[18:21], off
	s_cbranch_scc1 .LBB0_781
	s_add_i32 s43, s43, s33
	s_add_i32 s39, s39, s40
	s_cmpk_gt_i32 s43, 0xff
	s_cbranch_scc0 .LBB0_772

; __device__ __forceinline__ unsigned pk2(float lo, float hi) { f32x2 v = {lo, hi}; bf16x2_t b = __builtin_convertvector(v, bf16x2_t); return __builtin_bit_cast(unsigned, b); }
; __device__ __forceinline__ float bf_lo(unsigned u) { return __uint_as_float(u << 16); }
; __device__ __forceinline__ float bf_hi(unsigned u) { return __uint_as_float(u & 0xffff0000u); }
; __device__ __forceinline__ void lru_fix_item(const Ptrs& P, int it) {
;     ...
; #pragma unroll 4
;     for (int k = 0; k < 16; ++k) { const size_t row = (size_t)(b * SEQ + c * 64 + tg + 4 * k);
;         const u32x4 hw = *(const u32x4*)(P.HL() + row * 1024 + c8 * 8), cw = *(const u32x4*)(P.CA() + row * 1024 + c8 * 8), gw = *(const u32x4*)(P.PA() + row * NA + C_GC + c8 * 8);
;         u32x4 o;
;         o.x = pk2((bf_lo(hw.x) + bf_lo(cw.x) * H0[0]) * bf_lo(gw.x), (bf_hi(hw.x) + bf_hi(cw.x) * H0[1]) * bf_hi(gw.x));
;         o.y = pk2((bf_lo(hw.y) + bf_lo(cw.y) * H0[2]) * bf_lo(gw.y), (bf_hi(hw.y) + bf_hi(cw.y) * H0[3]) * bf_hi(gw.y));
;         o.z = pk2((bf_lo(hw.z) + bf_lo(cw.z) * H1[0]) * bf_lo(gw.z), (bf_hi(hw.z) + bf_hi(cw.z) * H1[1]) * bf_hi(gw.z));
;         o.w = pk2((bf_lo(hw.w) + bf_lo(cw.w) * H1[2]) * bf_lo(gw.w), (bf_hi(hw.w) + bf_hi(cw.w) * H1[3]) * bf_hi(gw.w));
;         *(u32x4*)(P.YC() + row * 1024 + c8 * 8) = o; }
.LBB0_1633:
	s_nop 0
	v_add_u32_e32 v18, s0, v1
	v_mov_b64_e32 v[20:21], s[14:15]
	v_mad_i64_i32 v[24:25], s[64:65], v18, s41, v[20:21]
	v_add_u32_e32 v26, 4, v18
	v_lshl_add_u64 v[32:33], v[24:25], 0, v[2:3]
	v_mad_i64_i32 v[24:25], s[64:65], v26, s41, v[20:21]
	v_add_co_u32_e32 v32, vcc, s42, v32
	v_ashrrev_i32_e32 v19, 31, v18
	v_add_u32_e32 v28, 8, v18
	v_lshl_add_u64 v[44:45], v[24:25], 0, v[2:3]
	v_addc_co_u32_e32 v33, vcc, 0, v33, vcc
	v_lshlrev_b64 v[30:31], 11, v[18:19]
	v_mad_i64_i32 v[34:35], s[64:65], v28, s41, v[20:21]
	v_add_co_u32_e32 v44, vcc, s42, v44
	v_ashrrev_i32_e32 v27, 31, v26
	v_ashrrev_i32_e32 v29, 31, v28
	v_lshl_add_u64 v[36:37], v[12:13], 0, v[30:31]
	v_lshl_add_u64 v[34:35], v[34:35], 0, v[2:3]
	v_addc_co_u32_e32 v45, vcc, 0, v45, vcc
	v_lshl_add_u64 v[38:39], v[14:15], 0, v[30:31]
	v_lshl_add_u64 v[40:41], v[16:17], 0, v[30:31]
	v_lshlrev_b64 v[42:43], 11, v[26:27]
	v_lshlrev_b64 v[46:47], 11, v[28:29]
	global_load_dwordx4 v[24:27], v[36:37], off
	global_load_dwordx4 v[28:31], v[38:39], off
	v_add_co_u32_e32 v52, vcc, s42, v34
	v_lshl_add_u64 v[36:37], v[12:13], 0, v[42:43]
	s_nop 0
	v_addc_co_u32_e32 v53, vcc, 0, v35, vcc
	global_load_dwordx4 v[32:35], v[32:33], off offset:3072
	v_lshl_add_u64 v[38:39], v[14:15], 0, v[42:43]
	v_lshl_add_u64 v[42:43], v[16:17], 0, v[42:43]
	v_lshl_add_u64 v[48:49], v[12:13], 0, v[46:47]
	v_lshl_add_u64 v[50:51], v[14:15], 0, v[46:47]
	v_add_u32_e32 v18, 12, v18
	v_ashrrev_i32_e32 v19, 31, v18
	v_mad_i64_i32 v[20:21], s[64:65], v18, s41, v[20:21]
	s_add_i32 s0, s0, 16
	s_cmp_lg_u32 s0, 64
	global_load_dwordx4 v[148:151], v[36:37], off
	global_load_dwordx4 v[152:155], v[38:39], off
	global_load_dwordx4 v[156:159], v[44:45], off offset:3072
	global_load_dwordx4 v[160:163], v[48:49], off
	global_load_dwordx4 v[164:167], v[50:51], off
	global_load_dwordx4 v[168:171], v[52:53], off offset:3072
	v_lshlrev_b64 v[184:185], 11, v[18:19]
	v_lshl_add_u64 v[186:187], v[20:21], 0, v[2:3]
	v_add_co_u32_e32 v190, vcc, s42, v186
	v_addc_co_u32_e32 v191, vcc, 0, v187, vcc
	v_lshl_add_u64 v[186:187], v[12:13], 0, v[184:185]
	v_lshl_add_u64 v[188:189], v[14:15], 0, v[184:185]
	global_load_dwordx4 v[172:175], v[186:187], off
	global_load_dwordx4 v[176:179], v[188:189], off
	global_load_dwordx4 v[180:183], v[190:191], off offset:3072
	s_waitcnt vmcnt(11)
	v_lshlrev_b32_e32 v54, 16, v24
	v_and_b32_e32 v55, 0xffff0000, v24
	s_waitcnt vmcnt(10)
	v_lshlrev_b32_e32 v56, 16, v28
	v_and_b32_e32 v57, 0xffff0000, v28
	v_lshlrev_b32_e32 v24, 16, v25
	v_and_b32_e32 v25, 0xffff0000, v25
	v_lshlrev_b32_e32 v28, 16, v29
	v_and_b32_e32 v29, 0xffff0000, v29
	v_lshlrev_b32_e32 v58, 16, v26
	v_and_b32_e32 v59, 0xffff0000, v26
	v_lshlrev_b32_e32 v60, 16, v30
	v_and_b32_e32 v61, 0xffff0000, v30
	v_lshlrev_b32_e32 v26, 16, v27
	v_and_b32_e32 v27, 0xffff0000, v27
	v_lshlrev_b32_e32 v30, 16, v31
	v_and_b32_e32 v31, 0xffff0000, v31
	v_pk_fma_f32 v[54:55], v[4:5], v[56:57], v[54:55]
	s_waitcnt vmcnt(9)
	v_lshlrev_b32_e32 v56, 16, v32
	v_and_b32_e32 v57, 0xffff0000, v32
	v_pk_fma_f32 v[24:25], v[6:7], v[28:29], v[24:25]
	v_lshlrev_b32_e32 v28, 16, v33
	v_and_b32_e32 v29, 0xffff0000, v33
	v_pk_fma_f32 v[32:33], v[8:9], v[60:61], v[58:59]
	v_lshlrev_b32_e32 v58, 16, v34
	v_and_b32_e32 v59, 0xffff0000, v34
	v_pk_fma_f32 v[26:27], v[10:11], v[30:31], v[26:27]
	v_lshlrev_b32_e32 v30, 16, v35
	v_and_b32_e32 v31, 0xffff0000, v35
	v_pk_mul_f32 v[34:35], v[54:55], v[56:57]
	v_pk_mul_f32 v[28:29], v[24:25], v[28:29]
	v_pk_mul_f32 v[32:33], v[32:33], v[58:59]
	v_pk_mul_f32 v[30:31], v[26:27], v[30:31]
	v_cvt_pk_bf16_f32 v24, v34, v35
	v_cvt_pk_bf16_f32 v25, v28, v29
	v_cvt_pk_bf16_f32 v26, v32, v33
	v_cvt_pk_bf16_f32 v27, v30, v31
	global_store_dwordx4 v[40:41], v[24:27], off
	s_nop 0
	s_nop 0
	s_nop 0
	s_nop 0
	s_waitcnt vmcnt(9)
	v_lshlrev_b32_e32 v36, 16, v148
	v_and_b32_e32 v37, 0xffff0000, v148
	s_waitcnt vmcnt(8)
	v_lshlrev_b32_e32 v38, 16, v152
	v_and_b32_e32 v39, 0xffff0000, v152
	v_lshlrev_b32_e32 v24, 16, v149
	v_and_b32_e32 v25, 0xffff0000, v149
	v_lshlrev_b32_e32 v28, 16, v153
	v_and_b32_e32 v29, 0xffff0000, v153
	v_lshlrev_b32_e32 v44, 16, v150
	v_and_b32_e32 v45, 0xffff0000, v150
	v_lshlrev_b32_e32 v54, 16, v154
	v_and_b32_e32 v55, 0xffff0000, v154
	v_lshlrev_b32_e32 v26, 16, v151
	v_and_b32_e32 v27, 0xffff0000, v151
	v_lshlrev_b32_e32 v30, 16, v155
	v_and_b32_e32 v31, 0xffff0000, v155
	s_waitcnt vmcnt(7)
; __device__ __forceinline__ unsigned pk2(float lo, float hi) { f32x2 v = {lo, hi}; bf16x2_t b = __builtin_convertvector(v, bf16x2_t); return __builtin_bit_cast(unsigned, b); }
; __device__ __forceinline__ float bf_lo(unsigned u) { return __uint_as_float(u << 16); }
; __device__ __forceinline__ float bf_hi(unsigned u) { return __uint_as_float(u & 0xffff0000u); }
; __device__ __forceinline__ void lru_fix_item(const Ptrs& P, int it) {
;     ...
; #pragma unroll 4
;     for (int k = 0; k < 16; ++k) { const size_t row = (size_t)(b * SEQ + c * 64 + tg + 4 * k);
;         const u32x4 hw = *(const u32x4*)(P.HL() + row * 1024 + c8 * 8), cw = *(const u32x4*)(P.CA() + row * 1024 + c8 * 8), gw = *(const u32x4*)(P.PA() + row * NA + C_GC + c8 * 8);
;         u32x4 o;
;         o.x = pk2((bf_lo(hw.x) + bf_lo(cw.x) * H0[0]) * bf_lo(gw.x), (bf_hi(hw.x) + bf_hi(cw.x) * H0[1]) * bf_hi(gw.x));
;         o.y = pk2((bf_lo(hw.y) + bf_lo(cw.y) * H0[2]) * bf_lo(gw.y), (bf_hi(hw.y) + bf_hi(cw.y) * H0[3]) * bf_hi(gw.y));
;         o.z = pk2((bf_lo(hw.z) + bf_lo(cw.z) * H1[0]) * bf_lo(gw.z), (bf_hi(hw.z) + bf_hi(cw.z) * H1[1]) * bf_hi(gw.z));
;         o.w = pk2((bf_lo(hw.w) + bf_lo(cw.w) * H1[2]) * bf_lo(gw.w), (bf_hi(hw.w) + bf_hi(cw.w) * H1[3]) * bf_hi(gw.w));
;         *(u32x4*)(P.YC() + row * 1024 + c8 * 8) = o; }
; template <int l> __device__ __forceinline__ void layer_phases(LAS unsigned char* lds, Ptrs& P, const XcdBarrier& xbar, KArgs kargs, const int lo, const int hi, const int lane0, const int wave, const int G0, const int bx0) {
;     ...
;             for (int it = bx; it < 256; it += G) lru_fix_item(P, it);
	v_lshlrev_b32_e32 v40, 16, v156
	v_and_b32_e32 v41, 0xffff0000, v156
	v_lshlrev_b32_e32 v32, 16, v157
	v_and_b32_e32 v33, 0xffff0000, v157
	v_lshlrev_b32_e32 v56, 16, v158
	v_and_b32_e32 v57, 0xffff0000, v158
	v_lshlrev_b32_e32 v34, 16, v159
	v_and_b32_e32 v35, 0xffff0000, v159
	v_pk_fma_f32 v[36:37], v[4:5], v[38:39], v[36:37]
	v_pk_fma_f32 v[24:25], v[6:7], v[28:29], v[24:25]
	v_pk_fma_f32 v[28:29], v[8:9], v[54:55], v[44:45]
	v_pk_fma_f32 v[26:27], v[10:11], v[30:31], v[26:27]
	v_pk_mul_f32 v[30:31], v[36:37], v[40:41]
	v_pk_mul_f32 v[32:33], v[24:25], v[32:33]
	v_pk_mul_f32 v[28:29], v[28:29], v[56:57]
	v_pk_mul_f32 v[34:35], v[26:27], v[34:35]
	v_cvt_pk_bf16_f32 v24, v30, v31
	v_cvt_pk_bf16_f32 v25, v32, v33
	v_cvt_pk_bf16_f32 v26, v28, v29
	v_cvt_pk_bf16_f32 v27, v34, v35
	global_store_dwordx4 v[42:43], v[24:27], off
	s_nop 0
	s_nop 0
	s_nop 0
	s_nop 0
	v_lshlrev_b64 v[36:37], 11, v[18:19]
	v_lshl_add_u64 v[18:19], v[20:21], 0, v[2:3]
	v_add_co_u32_e32 v44, vcc, s42, v18
	v_lshl_add_u64 v[38:39], v[16:17], 0, v[46:47]
	s_nop 0
	v_addc_co_u32_e32 v45, vcc, 0, v19, vcc
	v_lshl_add_u64 v[40:41], v[12:13], 0, v[36:37]
	v_lshl_add_u64 v[42:43], v[14:15], 0, v[36:37]
	s_waitcnt vmcnt(7)
	v_lshlrev_b32_e32 v18, 16, v160
	v_and_b32_e32 v19, 0xffff0000, v160
	s_waitcnt vmcnt(6)
	v_lshlrev_b32_e32 v20, 16, v164
	v_and_b32_e32 v21, 0xffff0000, v164
	v_lshlrev_b32_e32 v24, 16, v161
	v_and_b32_e32 v25, 0xffff0000, v161
	v_lshlrev_b32_e32 v28, 16, v165
	v_and_b32_e32 v29, 0xffff0000, v165
	v_lshlrev_b32_e32 v48, 16, v162
	v_and_b32_e32 v49, 0xffff0000, v162
	v_lshlrev_b32_e32 v50, 16, v166
	v_and_b32_e32 v51, 0xffff0000, v166
	v_lshlrev_b32_e32 v26, 16, v163
	v_and_b32_e32 v27, 0xffff0000, v163
	v_lshlrev_b32_e32 v30, 16, v167
	v_and_b32_e32 v31, 0xffff0000, v167
	s_waitcnt vmcnt(5)
	v_lshlrev_b32_e32 v46, 16, v168
	v_and_b32_e32 v47, 0xffff0000, v168
	v_lshlrev_b32_e32 v32, 16, v169
	v_and_b32_e32 v33, 0xffff0000, v169
	v_lshlrev_b32_e32 v52, 16, v170
	v_and_b32_e32 v53, 0xffff0000, v170
	v_lshlrev_b32_e32 v34, 16, v171
	v_and_b32_e32 v35, 0xffff0000, v171
	v_pk_fma_f32 v[18:19], v[4:5], v[20:21], v[18:19]
	v_pk_fma_f32 v[20:21], v[6:7], v[28:29], v[24:25]
	v_pk_fma_f32 v[24:25], v[8:9], v[50:51], v[48:49]
	v_pk_fma_f32 v[26:27], v[10:11], v[30:31], v[26:27]
	v_pk_mul_f32 v[18:19], v[18:19], v[46:47]
	v_pk_mul_f32 v[20:21], v[20:21], v[32:33]
	v_pk_mul_f32 v[24:25], v[24:25], v[52:53]
	v_pk_mul_f32 v[26:27], v[26:27], v[34:35]
	v_cvt_pk_bf16_f32 v18, v18, v19
	v_cvt_pk_bf16_f32 v19, v20, v21
	v_cvt_pk_bf16_f32 v20, v24, v25
	v_cvt_pk_bf16_f32 v21, v26, v27
	global_store_dwordx4 v[38:39], v[18:21], off
	s_nop 0
	s_nop 0
	s_nop 0
	s_nop 0
	v_lshl_add_u64 v[32:33], v[16:17], 0, v[36:37]
	s_waitcnt vmcnt(5)
	v_lshlrev_b32_e32 v34, 16, v172
	v_and_b32_e32 v35, 0xffff0000, v172
	s_waitcnt vmcnt(4)
	v_lshlrev_b32_e32 v36, 16, v176
	v_and_b32_e32 v37, 0xffff0000, v176
	v_lshlrev_b32_e32 v18, 16, v173
	v_and_b32_e32 v19, 0xffff0000, v173
	v_lshlrev_b32_e32 v24, 16, v177
	v_and_b32_e32 v25, 0xffff0000, v177
	v_lshlrev_b32_e32 v40, 16, v174
	v_and_b32_e32 v41, 0xffff0000, v174
	v_lshlrev_b32_e32 v42, 16, v178
	v_and_b32_e32 v43, 0xffff0000, v178
	v_lshlrev_b32_e32 v20, 16, v175
	v_and_b32_e32 v21, 0xffff0000, v175
	v_lshlrev_b32_e32 v26, 16, v179
	v_and_b32_e32 v27, 0xffff0000, v179
	s_waitcnt vmcnt(3)
	v_lshlrev_b32_e32 v38, 16, v180
	v_and_b32_e32 v39, 0xffff0000, v180
	v_lshlrev_b32_e32 v28, 16, v181
	v_and_b32_e32 v29, 0xffff0000, v181
	v_lshlrev_b32_e32 v44, 16, v182
	v_and_b32_e32 v45, 0xffff0000, v182
	v_lshlrev_b32_e32 v30, 16, v183
	v_and_b32_e32 v31, 0xffff0000, v183
	v_pk_fma_f32 v[34:35], v[4:5], v[36:37], v[34:35]
	v_pk_fma_f32 v[18:19], v[6:7], v[24:25], v[18:19]
	v_pk_fma_f32 v[24:25], v[8:9], v[42:43], v[40:41]
	v_pk_fma_f32 v[20:21], v[10:11], v[26:27], v[20:21]
	v_pk_mul_f32 v[26:27], v[34:35], v[38:39]
	v_pk_mul_f32 v[28:29], v[18:19], v[28:29]
	v_pk_mul_f32 v[24:25], v[24:25], v[44:45]
	v_pk_mul_f32 v[30:31], v[20:21], v[30:31]
	v_cvt_pk_bf16_f32 v18, v26, v27
	v_cvt_pk_bf16_f32 v19, v28, v29
	v_cvt_pk_bf16_f32 v20, v24, v25
	v_cvt_pk_bf16_f32 v21, v30, v31
	global_store_dwordx4 v[32:33], v[18:21], off
	s_cbranch_scc1 .LBB0_1633
	s_add_i32 s43, s43, s33
	s_add_i32 s39, s39, s40
	s_cmpk_gt_i32 s43, 0xff
	s_cbranch_scc0 .LBB0_1624
